# attention softmax: (s-m) subtractions and row-sum additions as packed-f32 adds (80 fewer VALU per item), exp2 unchanged
# speedup vs baseline: 1.0083x; 1.0046x over previous
.LBB0_1152:
	s_mov_b32 s69, s57
	s_mov_b32 s71, s57
	s_mov_b32 s73, s57
	s_mov_b32 s75, s57
	s_mov_b32 s77, s57
	s_mov_b32 s79, s57
	s_mov_b32 s81, s57
	v_lshl_add_u64 v[16:17], v[40:41], 0, s[56:57]
	v_lshl_add_u64 v[20:21], v[40:41], 0, s[68:69]
	v_lshl_add_u64 v[24:25], v[40:41], 0, s[70:71]
	v_lshl_add_u64 v[28:29], v[40:41], 0, s[72:73]
	v_lshl_add_u64 v[32:33], v[40:41], 0, s[74:75]
	v_lshl_add_u64 v[36:37], v[40:41], 0, s[76:77]
	v_lshl_add_u64 v[42:43], v[40:41], 0, s[78:79]
	v_lshl_add_u64 v[44:45], v[40:41], 0, s[80:81]
	global_load_dwordx4 v[16:19], v[16:17], off
	s_nop 0
	global_load_dwordx4 v[20:23], v[20:21], off
	s_nop 0
	global_load_dwordx4 v[24:27], v[24:25], off
	s_nop 0
	global_load_dwordx4 v[28:31], v[28:29], off
	s_nop 0
	global_load_dwordx4 v[32:35], v[32:33], off
	s_nop 0
	global_load_dwordx4 v[36:39], v[36:37], off
	s_nop 0
	global_load_dwordx4 v[40:43], v[42:43], off
	s_nop 0
	global_load_dwordx4 v[44:47], v[44:45], off
	v_max_f32_e32 v115, v115, v115
	v_max_f32_e32 v119, v119, v119
	v_mul_f32_e32 v120, v92, v159
	v_max_f32_e32 v115, v115, v119
	v_sub_f32_e32 v176, v115, v120
	v_pk_add_f32 v[100:101], v[100:101], v[176:177] op_sel_hi:[1,0] neg_lo:[0,1] neg_hi:[0,1]
	v_pk_add_f32 v[102:103], v[102:103], v[176:177] op_sel_hi:[1,0] neg_lo:[0,1] neg_hi:[0,1]
	v_pk_add_f32 v[104:105], v[104:105], v[176:177] op_sel_hi:[1,0] neg_lo:[0,1] neg_hi:[0,1]
	v_pk_add_f32 v[106:107], v[106:107], v[176:177] op_sel_hi:[1,0] neg_lo:[0,1] neg_hi:[0,1]
	v_pk_add_f32 v[108:109], v[108:109], v[176:177] op_sel_hi:[1,0] neg_lo:[0,1] neg_hi:[0,1]
	v_pk_add_f32 v[110:111], v[110:111], v[176:177] op_sel_hi:[1,0] neg_lo:[0,1] neg_hi:[0,1]
	v_pk_add_f32 v[112:113], v[112:113], v[176:177] op_sel_hi:[1,0] neg_lo:[0,1] neg_hi:[0,1]
	v_sub_f32_e32 v85, v85, v176
	v_sub_f32_e32 v114, v114, v176
	v_exp_f32_e32 v237, v85
	v_exp_f32_e32 v240, v100
	v_exp_f32_e32 v241, v102
	v_exp_f32_e32 v244, v101
	v_exp_f32_e32 v245, v104
	v_exp_f32_e32 v248, v103
	v_exp_f32_e32 v249, v106
	v_exp_f32_e32 v251, v105
	v_exp_f32_e32 v236, v108
	v_exp_f32_e32 v238, v107
	v_exp_f32_e32 v239, v110
	v_exp_f32_e32 v242, v109
	v_exp_f32_e32 v243, v112
	v_exp_f32_e32 v246, v111
	v_exp_f32_e32 v247, v114
	v_exp_f32_e32 v250, v113
	s_nop 0
	v_pk_add_f32 v[100:101], v[236:237], v[238:239]
	v_pk_add_f32 v[100:101], v[100:101], v[240:241]
	v_pk_add_f32 v[100:101], v[100:101], v[242:243]
	v_pk_add_f32 v[100:101], v[100:101], v[244:245]
	v_pk_add_f32 v[100:101], v[100:101], v[246:247]
	v_pk_add_f32 v[100:101], v[100:101], v[248:249]
	v_pk_add_f32 v[100:101], v[100:101], v[250:251]
	v_pk_add_f32 v[48:49], v[48:49], v[176:177] op_sel_hi:[1,0] neg_lo:[0,1] neg_hi:[0,1]
	v_pk_add_f32 v[50:51], v[50:51], v[176:177] op_sel_hi:[1,0] neg_lo:[0,1] neg_hi:[0,1]
	v_pk_add_f32 v[52:53], v[52:53], v[176:177] op_sel_hi:[1,0] neg_lo:[0,1] neg_hi:[0,1]
	v_pk_add_f32 v[54:55], v[54:55], v[176:177] op_sel_hi:[1,0] neg_lo:[0,1] neg_hi:[0,1]
	v_pk_add_f32 v[56:57], v[56:57], v[176:177] op_sel_hi:[1,0] neg_lo:[0,1] neg_hi:[0,1]
	v_pk_add_f32 v[58:59], v[58:59], v[176:177] op_sel_hi:[1,0] neg_lo:[0,1] neg_hi:[0,1]
	v_pk_add_f32 v[60:61], v[60:61], v[176:177] op_sel_hi:[1,0] neg_lo:[0,1] neg_hi:[0,1]
	v_pk_add_f32 v[62:63], v[62:63], v[176:177] op_sel_hi:[1,0] neg_lo:[0,1] neg_hi:[0,1]
	v_exp_f32_e32 v220, v48
	v_exp_f32_e32 v221, v49
	v_exp_f32_e32 v222, v50
	v_exp_f32_e32 v223, v51
	v_exp_f32_e32 v224, v52
	v_exp_f32_e32 v225, v53
	v_exp_f32_e32 v226, v54
	v_exp_f32_e32 v227, v55
	v_exp_f32_e32 v228, v56
	v_exp_f32_e32 v229, v57
	v_exp_f32_e32 v230, v58
	v_exp_f32_e32 v231, v59
	v_exp_f32_e32 v232, v60
	v_exp_f32_e32 v233, v61
	v_exp_f32_e32 v234, v62
	v_exp_f32_e32 v235, v63
	s_nop 0
	v_pk_add_f32 v[48:49], v[100:101], v[220:221]
	v_pk_add_f32 v[48:49], v[48:49], v[222:223]
	v_pk_add_f32 v[48:49], v[48:49], v[224:225]
	v_pk_add_f32 v[48:49], v[48:49], v[226:227]
	v_pk_add_f32 v[48:49], v[48:49], v[228:229]
	v_pk_add_f32 v[48:49], v[48:49], v[230:231]
	v_pk_add_f32 v[48:49], v[48:49], v[232:233]
	v_pk_add_f32 v[48:49], v[48:49], v[234:235]
	v_pk_add_f32 v[64:65], v[64:65], v[176:177] op_sel_hi:[1,0] neg_lo:[0,1] neg_hi:[0,1]
	v_pk_add_f32 v[66:67], v[66:67], v[176:177] op_sel_hi:[1,0] neg_lo:[0,1] neg_hi:[0,1]
	v_pk_add_f32 v[68:69], v[68:69], v[176:177] op_sel_hi:[1,0] neg_lo:[0,1] neg_hi:[0,1]
	v_pk_add_f32 v[70:71], v[70:71], v[176:177] op_sel_hi:[1,0] neg_lo:[0,1] neg_hi:[0,1]
	v_pk_add_f32 v[72:73], v[72:73], v[176:177] op_sel_hi:[1,0] neg_lo:[0,1] neg_hi:[0,1]
	v_pk_add_f32 v[74:75], v[74:75], v[176:177] op_sel_hi:[1,0] neg_lo:[0,1] neg_hi:[0,1]
	v_pk_add_f32 v[76:77], v[76:77], v[176:177] op_sel_hi:[1,0] neg_lo:[0,1] neg_hi:[0,1]
	v_pk_add_f32 v[78:79], v[78:79], v[176:177] op_sel_hi:[1,0] neg_lo:[0,1] neg_hi:[0,1]
	v_exp_f32_e32 v199, v64
	v_exp_f32_e32 v200, v65
	v_exp_f32_e32 v202, v66
	v_exp_f32_e32 v204, v67
	v_exp_f32_e32 v205, v68
	v_exp_f32_e32 v206, v69
	v_exp_f32_e32 v207, v70
	v_exp_f32_e32 v208, v71
	v_exp_f32_e32 v209, v72
	v_exp_f32_e32 v210, v73
	v_exp_f32_e32 v211, v74
	v_exp_f32_e32 v212, v75
	v_exp_f32_e32 v213, v76
	v_exp_f32_e32 v214, v77
	v_exp_f32_e32 v215, v78
	v_exp_f32_e32 v216, v79
	s_nop 0
	v_pk_add_f32 v[48:49], v[48:49], v[204:205]
	v_pk_add_f32 v[48:49], v[48:49], v[206:207]
	v_pk_add_f32 v[48:49], v[48:49], v[208:209]
	v_pk_add_f32 v[48:49], v[48:49], v[210:211]
	v_pk_add_f32 v[48:49], v[48:49], v[212:213]
	v_pk_add_f32 v[48:49], v[48:49], v[214:215]
	v_add_f32_e32 v50, 0, v199
	v_add_f32_e32 v50, v50, v200
	v_add_f32_e32 v50, v50, v202
	v_add_f32_e32 v50, v50, v216
	v_pk_add_f32 v[80:81], v[80:81], v[176:177] op_sel_hi:[1,0] neg_lo:[0,1] neg_hi:[0,1]
	v_pk_add_f32 v[82:83], v[82:83], v[176:177] op_sel_hi:[1,0] neg_lo:[0,1] neg_hi:[0,1]
	v_pk_add_f32 v[86:87], v[86:87], v[176:177] op_sel_hi:[1,0] neg_lo:[0,1] neg_hi:[0,1]
	v_pk_add_f32 v[88:89], v[88:89], v[176:177] op_sel_hi:[1,0] neg_lo:[0,1] neg_hi:[0,1]
	v_pk_add_f32 v[90:91], v[90:91], v[176:177] op_sel_hi:[1,0] neg_lo:[0,1] neg_hi:[0,1]
	v_pk_add_f32 v[94:95], v[94:95], v[176:177] op_sel_hi:[1,0] neg_lo:[0,1] neg_hi:[0,1]
	v_pk_add_f32 v[96:97], v[96:97], v[176:177] op_sel_hi:[1,0] neg_lo:[0,1] neg_hi:[0,1]
	v_pk_add_f32 v[98:99], v[98:99], v[176:177] op_sel_hi:[1,0] neg_lo:[0,1] neg_hi:[0,1]
	v_exp_f32_e32 v119, v80
	v_exp_f32_e32 v120, v81
	v_exp_f32_e32 v121, v82
	v_exp_f32_e32 v122, v83
	v_exp_f32_e32 v123, v86
	v_exp_f32_e32 v124, v87
	v_exp_f32_e32 v125, v88
	v_exp_f32_e32 v126, v89
	v_exp_f32_e32 v127, v90
	v_exp_f32_e32 v140, v91
	v_exp_f32_e32 v144, v94
	v_exp_f32_e32 v145, v95
	v_exp_f32_e32 v146, v96
	v_exp_f32_e32 v147, v97
	v_exp_f32_e32 v194, v98
	v_exp_f32_e32 v195, v99
	s_nop 0
	v_pk_add_f32 v[48:49], v[48:49], v[120:121]
	v_pk_add_f32 v[48:49], v[48:49], v[122:123]
	v_pk_add_f32 v[48:49], v[48:49], v[124:125]
	v_pk_add_f32 v[48:49], v[48:49], v[126:127]
	v_pk_add_f32 v[48:49], v[48:49], v[144:145]
	v_pk_add_f32 v[48:49], v[48:49], v[146:147]
	v_pk_add_f32 v[48:49], v[48:49], v[194:195]
	v_add_f32_e32 v50, v50, v119
	v_add_f32_e32 v50, v50, v140
	v_pk_add_f32 v[116:117], v[116:117], v[176:177] op_sel_hi:[1,0] neg_lo:[0,1] neg_hi:[0,1]
	v_pk_add_f32 v[142:143], v[142:143], v[176:177] op_sel_hi:[1,0] neg_lo:[0,1] neg_hi:[0,1]
	v_pk_add_f32 v[192:193], v[192:193], v[176:177] op_sel_hi:[1,0] neg_lo:[0,1] neg_hi:[0,1]
	v_pk_add_f32 v[196:197], v[196:197], v[176:177] op_sel_hi:[1,0] neg_lo:[0,1] neg_hi:[0,1]
	v_pk_add_f32 v[218:219], v[218:219], v[176:177] op_sel_hi:[1,0] neg_lo:[0,1] neg_hi:[0,1]
	v_sub_f32_e32 v118, v118, v176
	v_sub_f32_e32 v198, v198, v176
	v_sub_f32_e32 v201, v201, v176
	v_sub_f32_e32 v203, v203, v176
	v_sub_f32_e32 v217, v217, v176
	v_sub_f32_e32 v252, v252, v176
	v_exp_f32_e32 v100, v116
	v_exp_f32_e32 v101, v117
	v_exp_f32_e32 v102, v118
	v_exp_f32_e32 v103, v142
	v_exp_f32_e32 v104, v143
	v_exp_f32_e32 v105, v192
	v_exp_f32_e32 v106, v193
	v_exp_f32_e32 v107, v196
	v_exp_f32_e32 v108, v197
	v_exp_f32_e32 v109, v198
	v_exp_f32_e32 v110, v201
	v_exp_f32_e32 v111, v203
	v_exp_f32_e32 v112, v217
	v_exp_f32_e32 v113, v218
	v_exp_f32_e32 v114, v219
	v_exp_f32_e32 v116, v252
	s_nop 0
	v_pk_add_f32 v[48:49], v[48:49], v[100:101]
	v_pk_add_f32 v[48:49], v[48:49], v[102:103]
	v_pk_add_f32 v[48:49], v[48:49], v[104:105]
	v_pk_add_f32 v[48:49], v[48:49], v[106:107]
	v_pk_add_f32 v[48:49], v[48:49], v[108:109]
	v_pk_add_f32 v[48:49], v[48:49], v[110:111]
	v_pk_add_f32 v[48:49], v[48:49], v[112:113]
	v_add_f32_e32 v50, v50, v114
	v_add_f32_e32 v50, v50, v116
	v_add_f32_e32 v117, v48, v49
	s_nop 0
	v_add_f32_e32 v117, v117, v50
	s_barrier
	s_waitcnt vmcnt(8)
	ds_write_b128 v161, v[0:3]
	ds_write_b128 v161, v[8:11] offset:64
	ds_write_b128 v161, v[4:7] offset:128
	ds_write_b128 v161, v[12:15] offset:192
	s_waitcnt vmcnt(7)
	ds_write_b128 v161, v[16:19] offset:256
	s_waitcnt vmcnt(6)
	ds_write_b128 v161, v[20:23] offset:320
	s_waitcnt vmcnt(5)
	ds_write_b128 v161, v[24:27] offset:384
	s_waitcnt vmcnt(4)
	ds_write_b128 v161, v[28:31] offset:448
	s_waitcnt vmcnt(3)
	ds_write_b128 v161, v[32:35] offset:512
	s_waitcnt vmcnt(2)
	ds_write_b128 v161, v[36:39] offset:576
	s_waitcnt vmcnt(1)
	ds_write_b128 v161, v[40:43] offset:640
	s_waitcnt vmcnt(0)
	ds_write_b128 v161, v[44:47] offset:704
	v_mov_b32_e32 v0, v149
	s_waitcnt lgkmcnt(0)
	s_barrier
	v_mov_b32_e32 v3, v139
	v_ashrrev_i32_e32 v192, 4, v0
	v_and_b32_e32 v193, 15, v0
	v_add_u32_e32 v0, s4, v192
	s_load_dwordx2 s[4:5], s[8:9], 0x68
	v_lshlrev_b32_e32 v0, s40, v0
	v_add_u32_e32 v94, s47, v0
	v_ashrrev_i32_e32 v95, 31, v94
	v_lshlrev_b64 v[0:1], 12, v[94:95]
	s_waitcnt lgkmcnt(0)
	v_lshl_add_u64 v[0:1], s[4:5], 0, v[0:1]
	s_lshl_b32 s4, s46, 7
	s_ashr_i32 s5, s4, 31
	v_lshl_add_u64 v[0:1], s[4:5], 1, v[0:1]
	v_lshlrev_b32_e32 v2, 4, v193
	v_mov_b32_e32 v118, v117
	v_lshl_add_u64 v[142:143], v[0:1], 0, v[2:3]
	v_cndmask_b32_e64 v0, 0, 1, s[24:25]
	v_permlane32_swap_b32_e32 v117, v118
	v_cmp_ne_u32_e64 s[44:45], 1, v0
	s_andn2_b64 vcc, exec, s[24:25]
	v_mov_b32_e32 v85, 0
	v_mov_b32_e32 v86, 0
	v_mov_b32_e32 v87, 0
	s_cbranch_vccnz .LBB0_1154
	global_load_dwordx4 v[84:87], v[142:143], off
